# attention: lazy-rescale test on per-lane maxima before the cross-lane reduction (reduction only on the rescale path)
# speedup vs baseline: 1.0124x; 1.0124x over previous
; __device__ __forceinline__ float xmax16(float m) { const auto r = __builtin_amdgcn_permlane16_swap(__float_as_uint(m), __float_as_uint(m), false, false); return fmaxf(__uint_as_float(r[0]), __uint_as_float(r[1])); }
; __device__ __forceinline__ float xmax32(float m) { const auto r = __builtin_amdgcn_permlane32_swap(__float_as_uint(m), __float_as_uint(m), false, false); return fmaxf(__uint_as_float(r[0]), __uint_as_float(r[1])); }
; __device__ __forceinline__ void attn_unit(const Params& P, LAS unsigned char* lds, int bh, int qb) {
;     ...
;             float mx[2];
; #pragma unroll
;             for (int qk = 0; qk < 2; ++qk) { float m_ = fmaxf(fmaxf(s[0][qk][0], s[0][qk][1]), fmaxf(s[0][qk][2], s[0][qk][3]));
; #pragma unroll
;                 for (int kvb = 1; kvb < 4; ++kvb) m_ = fmaxf(m_, fmaxf(fmaxf(s[kvb][qk][0], s[kvb][qk][1]), fmaxf(s[kvb][qk][2], s[kvb][qk][3])));
;                 m_ = xmax16(m_); m_ = xmax32(m_); mx[qk] = m_; }
;             if (t == 0 || __any((mx[0] > AT_THR) || (mx[1] > AT_THR))) {
; #pragma unroll
;                 for (int qk = 0; qk < 2; ++qk) { const float dl = (t == 0) ? mx[qk] : fmaxf(mx[qk], 0.f), alpha = __builtin_amdgcn_exp2f(-dl); mrow[qk] += dl; lacc[qk] *= alpha;
.LBB0_645:
	v_max3_f32 v207, v164, v165, v166
	v_max3_f32 v206, v148, v149, v150
	v_max3_f32 v207, v207, v167, v160
	v_max3_f32 v206, v206, v151, v144
	v_max3_f32 v207, v207, v161, v162
	v_max3_f32 v206, v206, v145, v146
	v_max3_f32 v207, v207, v163, v156
	v_max3_f32 v206, v206, v147, v140
	v_max3_f32 v207, v207, v157, v158
	v_max3_f32 v206, v206, v141, v142
	v_max3_f32 v207, v207, v159, v152
	v_max3_f32 v206, v206, v143, v136
	v_max3_f32 v207, v207, v153, v154
	v_max3_f32 v206, v206, v137, v138
	v_max_f32_e32 v207, v207, v155
	v_max_f32_e32 v206, v206, v139
	s_cmp_eq_u32 s85, 0
	s_cbranch_scc1 .Latt_slowmax
	v_max_f32_e32 v225, v207, v206
	s_mov_b32 s53, 0x41000000
	s_nop 0
	v_cmp_lt_f32_e32 vcc, s53, v225
	s_cbranch_vccz .LBB0_631
.Latt_slowmax:
	v_mov_b32_e32 v224, v207
	v_mov_b32_e32 v225, v206
	s_nop 0
	v_permlane16_swap_b32_e32 v207, v224
	v_permlane16_swap_b32_e32 v206, v225
	v_max_f32_e32 v207, v207, v224
	v_max_f32_e32 v206, v206, v225
	v_mov_b32_e32 v224, v207
	v_mov_b32_e32 v225, v206
	s_nop 0
	v_permlane32_swap_b32_e32 v207, v224
	v_permlane32_swap_b32_e32 v206, v225
	v_max_f32_e32 v207, v207, v224
	v_max_f32_e32 v206, v206, v225
	s_cmp_eq_u32 s85, 0
	s_cselect_b64 s[0:1], -1, 0
	s_mov_b64 s[54:55], -1
	s_and_b64 vcc, exec, s[0:1]
	v_mov_b32_e32 v224, v206
	s_cbranch_vccnz .LBB0_648
	v_max_f32_e32 v207, v207, v207
	v_max_f32_e32 v225, v207, v224
	s_mov_b32 s53, 0x41000000
	v_cmp_lt_f32_e32 vcc, s53, v225
	s_cbranch_vccz .LBB0_656
	v_max_f32_e32 v207, 0, v207
